# ffn_in epilogue: moved 43 s_mov s48 constants into the trans-op hazard s_nop slot after v_exp of the next output (one fewer issue slot per store)
# speedup vs baseline: 1.0017x; 1.0017x over previous
; DEV float silu(float x) { return x * sigm(x); }
; template <bool RES, class Epi>
; DEV void gemm_tile_x(const bf16_t* A0, int lda0, const bf16_t* A1, int lda1, int ksplit,
;                      const bf16_t* Bt, int ldb, int K, char* smem, const float* resb, Epi epi) {
;     ...
;   const int rl = wm * 128 + 4 * (lane >> 5);
;   const int col = wn * 64 + (lane & 31);
;   const unsigned resoff = (unsigned)(rl * DM + col);
; #pragma unroll
;   for (int mi = 0; mi < 4; ++mi) {
; #pragma unroll
;     for (int rh = 0; rh < 2; ++rh) {
;       float x0[8], x1[8];
;       if (RES) {
; #pragma unroll
;         for (int r8 = 0; r8 < 8; ++r8) {
;           const int r = rh * 8 + r8;
;           const int ru = mi * 32 + (r & 3) + 8 * (r >> 2);
;           const float* rp = resb + ru * DM;
;           x0[r8] = rp[resoff];
;           x1[r8] = rp[resoff + 32];
;         }
;       }
; #pragma unroll
;       for (int r8 = 0; r8 < 8; ++r8) {
;         const int r = rh * 8 + r8;
;         const int ru = mi * 32 + (r & 3) + 8 * (r >> 2);
;         if (RES) epi(ru, rl, col, acc[mi][0][r], acc[mi][1][r], x0[r8], x1[r8]);
;         else epi(ru, rl, col, acc[mi][0][r], acc[mi][1][r], 0.f, 0.f);
;         if ((r8 & 3) == 3) __builtin_amdgcn_sched_barrier(0);
;       }
; DEV void phase_ffn_in(const Params& p, const bf16_t* wt, char* smem) {
;     ...
;     bf16_t* hb = h + (size_t)rt * TM * DFF + ct * 64;
;     gemm_tile(xb + (size_t)rt * TM * DM, DM, nullptr, 0, DM, wt + (size_t)ct * 128 * DM, DM, DM, smem,
;               [&](int ru, int rl, int c, float v0, float v1) {
;                 (hb + ru * DFF)[(unsigned)(rl * DFF + (c >> 6) * 32 + (c & 31))] = f2bf(silu(v0) * v1);
;               });
.LBB0_174:
	s_waitcnt vmcnt(5)
	v_mul_f32_e32 v128, 0xbfb8aa3b, v112
	v_exp_f32_e32 v128, v128
	s_lshl_b32 s52, s52, 6
	s_mul_hi_u32 s54, s48, 0x160000
	s_mul_i32 s48, s48, 0x160000
	v_add_f32_e32 v128, 1.0, v128
	v_rcp_f32_e32 v128, v128
	s_ashr_i32 s53, s52, 31
	s_add_u32 s48, s84, s48
	s_addc_u32 s54, s85, s54
	s_lshl_b64 s[52:53], s[52:53], 1
	s_add_u32 s52, s48, s52
	v_mul_f32_e32 v112, v112, v128
	s_addc_u32 s53, s54, s53
	v_mul_f32_e32 v96, v96, v112
	v_cvt_pk_bf16_f32 v96, v96, s0
	v_lshl_add_u64 v[128:129], v[182:183], 1, s[52:53]
	global_store_short v[128:129], v96, off
	v_mul_f32_e32 v96, 0xbfb8aa3b, v113
	v_exp_f32_e32 v96, v96
	s_movk_i32 s48, 0x1000
	v_add_f32_e32 v96, 1.0, v96
	v_rcp_f32_e32 v96, v96
	s_nop 0
	v_mul_f32_e32 v96, v113, v96
	v_mul_f32_e32 v96, v97, v96
	v_cvt_pk_bf16_f32 v112, v96, s0
	v_lshl_add_u64 v[96:97], v[128:129], 0, s[48:49]
	global_store_short v[96:97], v112, off offset:1536
	v_mul_f32_e32 v96, 0xbfb8aa3b, v114
	v_exp_f32_e32 v96, v96
	s_movk_i32 s48, 0x2000
	v_add_f32_e32 v96, 1.0, v96
	v_rcp_f32_e32 v96, v96
	s_nop 0
	v_mul_f32_e32 v96, v114, v96
	v_mul_f32_e32 v96, v98, v96
	v_cvt_pk_bf16_f32 v98, v96, s0
	v_lshl_add_u64 v[96:97], v[128:129], 0, s[48:49]
	global_store_short v[96:97], v98, off offset:3072
	v_mul_f32_e32 v96, 0xbfb8aa3b, v115
	v_exp_f32_e32 v96, v96
	s_movk_i32 s48, 0x4000
	v_add_f32_e32 v96, 1.0, v96
	v_rcp_f32_e32 v96, v96
	s_nop 0
	v_mul_f32_e32 v96, v115, v96
	v_mul_f32_e32 v96, v99, v96
	v_cvt_pk_bf16_f32 v98, v96, s0
	v_lshl_add_u64 v[96:97], v[128:129], 0, s[48:49]
	global_store_short v[96:97], v98, off offset:512
	v_mul_f32_e32 v96, 0xbfb8aa3b, v116
	v_exp_f32_e32 v96, v96
	s_mov_b32 s48, 0xb000
	v_add_f32_e32 v96, 1.0, v96
	v_rcp_f32_e32 v96, v96
	s_nop 0
	v_mul_f32_e32 v96, v116, v96
	v_mul_f32_e32 v96, v100, v96
	v_cvt_pk_bf16_f32 v98, v96, s0
	v_lshl_add_u64 v[96:97], v[128:129], 0, s[48:49]
	global_store_short v[96:97], v98, off
	v_mul_f32_e32 v96, 0xbfb8aa3b, v117
	v_exp_f32_e32 v96, v96
	s_mov_b32 s48, 0xc000
	v_add_f32_e32 v96, 1.0, v96
	v_rcp_f32_e32 v96, v96
	s_nop 0
	v_mul_f32_e32 v96, v117, v96
	v_mul_f32_e32 v96, v101, v96
	v_cvt_pk_bf16_f32 v98, v96, s0
	v_lshl_add_u64 v[96:97], v[128:129], 0, s[48:49]
	global_store_short v[96:97], v98, off offset:1536
	v_mul_f32_e32 v96, 0xbfb8aa3b, v118
	v_exp_f32_e32 v96, v96
	s_mov_b32 s48, 0xd000
	v_add_f32_e32 v96, 1.0, v96
	v_rcp_f32_e32 v96, v96
	s_nop 0
	v_mul_f32_e32 v96, v118, v96
	v_mul_f32_e32 v96, v102, v96
	v_cvt_pk_bf16_f32 v98, v96, s0
	v_lshl_add_u64 v[96:97], v[128:129], 0, s[48:49]
	global_store_short v[96:97], v98, off offset:3072
	v_mul_f32_e32 v96, 0xbfb8aa3b, v119
	v_exp_f32_e32 v96, v96
	s_mov_b32 s48, 0xf000
	v_add_f32_e32 v96, 1.0, v96
	v_rcp_f32_e32 v96, v96
	s_nop 0
	v_mul_f32_e32 v96, v119, v96
	v_mul_f32_e32 v96, v103, v96
	v_cvt_pk_bf16_f32 v98, v96, s0
	v_lshl_add_u64 v[96:97], v[128:129], 0, s[48:49]
	global_store_short v[96:97], v98, off offset:512
	v_mul_f32_e32 v96, 0xbfb8aa3b, v120
	v_exp_f32_e32 v96, v96
	s_mov_b32 s48, 0x16000
	v_add_f32_e32 v96, 1.0, v96
	v_rcp_f32_e32 v96, v96
	s_nop 0
	v_mul_f32_e32 v96, v120, v96
	v_mul_f32_e32 v96, v104, v96
	v_cvt_pk_bf16_f32 v98, v96, s0
	v_lshl_add_u64 v[96:97], v[128:129], 0, s[48:49]
	global_store_short v[96:97], v98, off
	v_mul_f32_e32 v96, 0xbfb8aa3b, v121
	v_exp_f32_e32 v96, v96
	s_mov_b32 s48, 0x17000
	v_add_f32_e32 v96, 1.0, v96
	v_rcp_f32_e32 v96, v96
	s_nop 0
	v_mul_f32_e32 v96, v121, v96
	v_mul_f32_e32 v96, v105, v96
	v_cvt_pk_bf16_f32 v98, v96, s0
	v_lshl_add_u64 v[96:97], v[128:129], 0, s[48:49]
	global_store_short v[96:97], v98, off offset:1536
	v_mul_f32_e32 v96, 0xbfb8aa3b, v122
	v_exp_f32_e32 v96, v96
	s_mov_b32 s48, 0x18000
	v_add_f32_e32 v96, 1.0, v96
	v_rcp_f32_e32 v96, v96
	s_nop 0
	v_mul_f32_e32 v96, v122, v96
	v_mul_f32_e32 v96, v106, v96
	v_cvt_pk_bf16_f32 v98, v96, s0
	v_lshl_add_u64 v[96:97], v[128:129], 0, s[48:49]
	global_store_short v[96:97], v98, off offset:3072
	v_mul_f32_e32 v96, 0xbfb8aa3b, v123
	v_exp_f32_e32 v96, v96
	s_mov_b32 s48, 0x1a000
	v_add_f32_e32 v96, 1.0, v96
	v_rcp_f32_e32 v96, v96
	s_nop 0
	v_mul_f32_e32 v96, v123, v96
	v_mul_f32_e32 v96, v107, v96
	v_cvt_pk_bf16_f32 v98, v96, s0
	v_lshl_add_u64 v[96:97], v[128:129], 0, s[48:49]
	global_store_short v[96:97], v98, off offset:512
	v_mul_f32_e32 v96, 0xbfb8aa3b, v124
	v_exp_f32_e32 v96, v96
	s_mov_b32 s48, 0x21000
	v_add_f32_e32 v96, 1.0, v96
	v_rcp_f32_e32 v96, v96
	s_nop 0
	v_mul_f32_e32 v96, v124, v96
	v_mul_f32_e32 v96, v108, v96
	v_cvt_pk_bf16_f32 v98, v96, s0
	v_lshl_add_u64 v[96:97], v[128:129], 0, s[48:49]
	global_store_short v[96:97], v98, off
	v_mul_f32_e32 v96, 0xbfb8aa3b, v125
	v_exp_f32_e32 v96, v96
	s_mov_b32 s48, 0x22000
	v_add_f32_e32 v96, 1.0, v96
	v_rcp_f32_e32 v96, v96
	s_nop 0
	v_mul_f32_e32 v96, v125, v96
	v_mul_f32_e32 v96, v109, v96
	v_cvt_pk_bf16_f32 v98, v96, s0
	v_lshl_add_u64 v[96:97], v[128:129], 0, s[48:49]
	global_store_short v[96:97], v98, off offset:1536
	v_mul_f32_e32 v96, 0xbfb8aa3b, v126
	v_exp_f32_e32 v96, v96
	s_mov_b32 s48, 0x23000
	v_add_f32_e32 v96, 1.0, v96
	v_rcp_f32_e32 v96, v96
	s_nop 0
	v_mul_f32_e32 v96, v126, v96
	v_mul_f32_e32 v96, v110, v96
	v_cvt_pk_bf16_f32 v98, v96, s0
	v_lshl_add_u64 v[96:97], v[128:129], 0, s[48:49]
	global_store_short v[96:97], v98, off offset:3072
	v_mul_f32_e32 v96, 0xbfb8aa3b, v127
	v_exp_f32_e32 v96, v96
	s_mov_b32 s48, 0x25000
	v_add_f32_e32 v96, 1.0, v96
	v_rcp_f32_e32 v96, v96
	s_nop 0
	v_mul_f32_e32 v96, v127, v96
	v_mul_f32_e32 v96, v111, v96
	v_cvt_pk_bf16_f32 v98, v96, s0
	v_lshl_add_u64 v[96:97], v[128:129], 0, s[48:49]
	global_store_short v[96:97], v98, off offset:512
; DEV float silu(float x) { return x * sigm(x); }
; template <bool RES, class Epi>
; DEV void gemm_tile_x(const bf16_t* A0, int lda0, const bf16_t* A1, int lda1, int ksplit,
;                      const bf16_t* Bt, int ldb, int K, char* smem, const float* resb, Epi epi) {
;     ...
;   for (int mi = 0; mi < 4; ++mi) {
; #pragma unroll
;     for (int rh = 0; rh < 2; ++rh) {
;       float x0[8], x1[8];
;       if (RES) {
; #pragma unroll
;         for (int r8 = 0; r8 < 8; ++r8) {
;           const int r = rh * 8 + r8;
;           const int ru = mi * 32 + (r & 3) + 8 * (r >> 2);
;           const float* rp = resb + ru * DM;
;           x0[r8] = rp[resoff];
;           x1[r8] = rp[resoff + 32];
;         }
;       }
; #pragma unroll
;       for (int r8 = 0; r8 < 8; ++r8) {
;         const int r = rh * 8 + r8;
;         const int ru = mi * 32 + (r & 3) + 8 * (r >> 2);
;         if (RES) epi(ru, rl, col, acc[mi][0][r], acc[mi][1][r], x0[r8], x1[r8]);
;         else epi(ru, rl, col, acc[mi][0][r], acc[mi][1][r], 0.f, 0.f);
;         if ((r8 & 3) == 3) __builtin_amdgcn_sched_barrier(0);
;       }
; DEV void phase_ffn_in(const Params& p, const bf16_t* wt, char* smem) {
;     ...
;               [&](int ru, int rl, int c, float v0, float v1) {
;                 (hb + ru * DFF)[(unsigned)(rl * DFF + (c >> 6) * 32 + (c & 31))] = f2bf(silu(v0) * v1);
;               });
	v_mul_f32_e32 v96, 0xbfb8aa3b, v80
	v_exp_f32_e32 v96, v96
	s_mov_b32 s48, 0x2c000
	v_add_f32_e32 v96, 1.0, v96
	v_rcp_f32_e32 v96, v96
	s_nop 0
	v_mul_f32_e32 v80, v80, v96
	v_mul_f32_e32 v64, v64, v80
	v_lshl_add_u64 v[96:97], v[128:129], 0, s[48:49]
	v_cvt_pk_bf16_f32 v64, v64, s0
	s_nop 0
	global_store_short v[96:97], v64, off
	v_mul_f32_e32 v64, 0xbfb8aa3b, v81
	v_exp_f32_e32 v64, v64
	s_mov_b32 s48, 0x2d000
	v_add_f32_e32 v64, 1.0, v64
	v_rcp_f32_e32 v64, v64
	s_nop 0
	v_mul_f32_e32 v64, v81, v64
	v_mul_f32_e32 v64, v65, v64
	v_cvt_pk_bf16_f32 v80, v64, s0
	v_lshl_add_u64 v[64:65], v[128:129], 0, s[48:49]
	global_store_short v[64:65], v80, off offset:1536
	v_mul_f32_e32 v64, 0xbfb8aa3b, v82
	v_exp_f32_e32 v64, v64
	s_mov_b32 s48, 0x2e000
	v_add_f32_e32 v64, 1.0, v64
	v_rcp_f32_e32 v64, v64
	s_nop 0
	v_mul_f32_e32 v64, v82, v64
	v_mul_f32_e32 v64, v66, v64
	v_cvt_pk_bf16_f32 v66, v64, s0
	v_lshl_add_u64 v[64:65], v[128:129], 0, s[48:49]
	global_store_short v[64:65], v66, off offset:3072
	v_mul_f32_e32 v64, 0xbfb8aa3b, v83
	v_exp_f32_e32 v64, v64
	s_mov_b32 s48, 0x30000
	v_add_f32_e32 v64, 1.0, v64
	v_rcp_f32_e32 v64, v64
	s_nop 0
	v_mul_f32_e32 v64, v83, v64
	v_mul_f32_e32 v64, v67, v64
	v_cvt_pk_bf16_f32 v66, v64, s0
	v_lshl_add_u64 v[64:65], v[128:129], 0, s[48:49]
	global_store_short v[64:65], v66, off offset:512
	v_mul_f32_e32 v64, 0xbfb8aa3b, v84
	v_exp_f32_e32 v64, v64
	s_mov_b32 s48, 0x37000
	v_add_f32_e32 v64, 1.0, v64
	v_rcp_f32_e32 v64, v64
	s_nop 0
	v_mul_f32_e32 v64, v84, v64
	v_mul_f32_e32 v64, v68, v64
	v_cvt_pk_bf16_f32 v66, v64, s0
	v_lshl_add_u64 v[64:65], v[128:129], 0, s[48:49]
	global_store_short v[64:65], v66, off
	v_mul_f32_e32 v64, 0xbfb8aa3b, v85
	v_exp_f32_e32 v64, v64
	s_mov_b32 s48, 0x38000
	v_add_f32_e32 v64, 1.0, v64
	v_rcp_f32_e32 v64, v64
	s_nop 0
	v_mul_f32_e32 v64, v85, v64
	v_mul_f32_e32 v64, v69, v64
	v_cvt_pk_bf16_f32 v66, v64, s0
	v_lshl_add_u64 v[64:65], v[128:129], 0, s[48:49]
	global_store_short v[64:65], v66, off offset:1536
	v_mul_f32_e32 v64, 0xbfb8aa3b, v86
	v_exp_f32_e32 v64, v64
	s_mov_b32 s48, 0x39000
	v_add_f32_e32 v64, 1.0, v64
	v_rcp_f32_e32 v64, v64
	s_nop 0
	v_mul_f32_e32 v64, v86, v64
	v_mul_f32_e32 v64, v70, v64
	v_cvt_pk_bf16_f32 v66, v64, s0
	v_lshl_add_u64 v[64:65], v[128:129], 0, s[48:49]
	global_store_short v[64:65], v66, off offset:3072
	v_mul_f32_e32 v64, 0xbfb8aa3b, v87
	v_exp_f32_e32 v64, v64
	s_mov_b32 s48, 0x3b000
	v_add_f32_e32 v64, 1.0, v64
	v_rcp_f32_e32 v64, v64
	s_nop 0
	v_mul_f32_e32 v64, v87, v64
	v_mul_f32_e32 v64, v71, v64
	v_cvt_pk_bf16_f32 v66, v64, s0
	v_lshl_add_u64 v[64:65], v[128:129], 0, s[48:49]
	global_store_short v[64:65], v66, off offset:512
	v_mul_f32_e32 v64, 0xbfb8aa3b, v88
	v_exp_f32_e32 v64, v64
	s_mov_b32 s48, 0x42000
	v_add_f32_e32 v64, 1.0, v64
	v_rcp_f32_e32 v64, v64
	s_nop 0
	v_mul_f32_e32 v64, v88, v64
	v_mul_f32_e32 v64, v72, v64
	v_cvt_pk_bf16_f32 v66, v64, s0
	v_lshl_add_u64 v[64:65], v[128:129], 0, s[48:49]
	global_store_short v[64:65], v66, off
	v_mul_f32_e32 v64, 0xbfb8aa3b, v89
	v_exp_f32_e32 v64, v64
	s_mov_b32 s48, 0x43000
	v_add_f32_e32 v64, 1.0, v64
	v_rcp_f32_e32 v64, v64
	s_nop 0
	v_mul_f32_e32 v64, v89, v64
	v_mul_f32_e32 v64, v73, v64
	v_cvt_pk_bf16_f32 v66, v64, s0
	v_lshl_add_u64 v[64:65], v[128:129], 0, s[48:49]
	global_store_short v[64:65], v66, off offset:1536
	v_mul_f32_e32 v64, 0xbfb8aa3b, v90
	v_exp_f32_e32 v64, v64
	s_mov_b32 s48, 0x44000
	v_add_f32_e32 v64, 1.0, v64
	v_rcp_f32_e32 v64, v64
	s_nop 0
	v_mul_f32_e32 v64, v90, v64
	v_mul_f32_e32 v64, v74, v64
	v_cvt_pk_bf16_f32 v66, v64, s0
	v_lshl_add_u64 v[64:65], v[128:129], 0, s[48:49]
	global_store_short v[64:65], v66, off offset:3072
	v_mul_f32_e32 v64, 0xbfb8aa3b, v91
	v_exp_f32_e32 v64, v64
	s_mov_b32 s48, 0x46000
	v_add_f32_e32 v64, 1.0, v64
	v_rcp_f32_e32 v64, v64
	s_nop 0
	v_mul_f32_e32 v64, v91, v64
	v_mul_f32_e32 v64, v75, v64
	v_cvt_pk_bf16_f32 v66, v64, s0
	v_lshl_add_u64 v[64:65], v[128:129], 0, s[48:49]
	global_store_short v[64:65], v66, off offset:512
	v_mul_f32_e32 v64, 0xbfb8aa3b, v92
	v_exp_f32_e32 v64, v64
	s_mov_b32 s48, 0x4d000
	v_add_f32_e32 v64, 1.0, v64
	v_rcp_f32_e32 v64, v64
	s_nop 0
	v_mul_f32_e32 v64, v92, v64
	v_mul_f32_e32 v64, v76, v64
	v_cvt_pk_bf16_f32 v66, v64, s0
	v_lshl_add_u64 v[64:65], v[128:129], 0, s[48:49]
	global_store_short v[64:65], v66, off
	v_mul_f32_e32 v64, 0xbfb8aa3b, v93
	v_exp_f32_e32 v64, v64
	s_mov_b32 s48, 0x4e000
	v_add_f32_e32 v64, 1.0, v64
	v_rcp_f32_e32 v64, v64
	s_nop 0
	v_mul_f32_e32 v64, v93, v64
	v_mul_f32_e32 v64, v77, v64
	v_cvt_pk_bf16_f32 v66, v64, s0
	v_lshl_add_u64 v[64:65], v[128:129], 0, s[48:49]
	global_store_short v[64:65], v66, off offset:1536
	v_mul_f32_e32 v64, 0xbfb8aa3b, v94
	v_exp_f32_e32 v64, v64
	s_mov_b32 s48, 0x4f000
	v_add_f32_e32 v64, 1.0, v64
	v_rcp_f32_e32 v64, v64
	s_nop 0
	v_mul_f32_e32 v64, v94, v64
	v_mul_f32_e32 v64, v78, v64
	v_cvt_pk_bf16_f32 v66, v64, s0
	v_lshl_add_u64 v[64:65], v[128:129], 0, s[48:49]
	global_store_short v[64:65], v66, off offset:3072
	v_mul_f32_e32 v64, 0xbfb8aa3b, v95
	v_exp_f32_e32 v64, v64
	s_mov_b32 s48, 0x51000
	v_add_f32_e32 v64, 1.0, v64
	v_rcp_f32_e32 v64, v64
	s_nop 0
	v_mul_f32_e32 v64, v95, v64
	v_mul_f32_e32 v64, v79, v64
	v_cvt_pk_bf16_f32 v66, v64, s0
	v_lshl_add_u64 v[64:65], v[128:129], 0, s[48:49]
	global_store_short v[64:65], v66, off offset:512
	v_mul_f32_e32 v64, 0xbfb8aa3b, v48
	v_exp_f32_e32 v64, v64
	s_mov_b32 s48, 0x58000
	v_add_f32_e32 v64, 1.0, v64
	v_rcp_f32_e32 v64, v64
	s_nop 0
	v_mul_f32_e32 v48, v48, v64
	v_mul_f32_e32 v32, v32, v48
	v_lshl_add_u64 v[64:65], v[128:129], 0, s[48:49]
	v_cvt_pk_bf16_f32 v32, v32, s0
	s_nop 0
; DEV float silu(float x) { return x * sigm(x); }
; template <bool RES, class Epi>
; DEV void gemm_tile_x(const bf16_t* A0, int lda0, const bf16_t* A1, int lda1, int ksplit,
;                      const bf16_t* Bt, int ldb, int K, char* smem, const float* resb, Epi epi) {
;     ...
;   for (int mi = 0; mi < 4; ++mi) {
; #pragma unroll
;     for (int rh = 0; rh < 2; ++rh) {
;       float x0[8], x1[8];
;       if (RES) {
; #pragma unroll
;         for (int r8 = 0; r8 < 8; ++r8) {
;           const int r = rh * 8 + r8;
;           const int ru = mi * 32 + (r & 3) + 8 * (r >> 2);
;           const float* rp = resb + ru * DM;
;           x0[r8] = rp[resoff];
;           x1[r8] = rp[resoff + 32];
;         }
;       }
; #pragma unroll
;       for (int r8 = 0; r8 < 8; ++r8) {
;         const int r = rh * 8 + r8;
;         const int ru = mi * 32 + (r & 3) + 8 * (r >> 2);
;         if (RES) epi(ru, rl, col, acc[mi][0][r], acc[mi][1][r], x0[r8], x1[r8]);
;         else epi(ru, rl, col, acc[mi][0][r], acc[mi][1][r], 0.f, 0.f);
;         if ((r8 & 3) == 3) __builtin_amdgcn_sched_barrier(0);
;       }
; DEV void phase_ffn_in(const Params& p, const bf16_t* wt, char* smem) {
;     ...
;               [&](int ru, int rl, int c, float v0, float v1) {
;                 (hb + ru * DFF)[(unsigned)(rl * DFF + (c >> 6) * 32 + (c & 31))] = f2bf(silu(v0) * v1);
;               });
	global_store_short v[64:65], v32, off
	v_mul_f32_e32 v32, 0xbfb8aa3b, v49
	v_exp_f32_e32 v32, v32
	s_mov_b32 s48, 0x59000
	v_add_f32_e32 v32, 1.0, v32
	v_rcp_f32_e32 v32, v32
	s_nop 0
	v_mul_f32_e32 v32, v49, v32
	v_mul_f32_e32 v32, v33, v32
	v_cvt_pk_bf16_f32 v48, v32, s0
	v_lshl_add_u64 v[32:33], v[128:129], 0, s[48:49]
	global_store_short v[32:33], v48, off offset:1536
	v_mul_f32_e32 v32, 0xbfb8aa3b, v50
	v_exp_f32_e32 v32, v32
	s_mov_b32 s48, 0x5a000
	v_add_f32_e32 v32, 1.0, v32
	v_rcp_f32_e32 v32, v32
	s_nop 0
	v_mul_f32_e32 v32, v50, v32
	v_mul_f32_e32 v32, v34, v32
	v_cvt_pk_bf16_f32 v34, v32, s0
	v_lshl_add_u64 v[32:33], v[128:129], 0, s[48:49]
	global_store_short v[32:33], v34, off offset:3072
	v_mul_f32_e32 v32, 0xbfb8aa3b, v51
	v_exp_f32_e32 v32, v32
	s_mov_b32 s48, 0x5c000
	v_add_f32_e32 v32, 1.0, v32
	v_rcp_f32_e32 v32, v32
	s_nop 0
	v_mul_f32_e32 v32, v51, v32
	v_mul_f32_e32 v32, v35, v32
	v_cvt_pk_bf16_f32 v34, v32, s0
	v_lshl_add_u64 v[32:33], v[128:129], 0, s[48:49]
	global_store_short v[32:33], v34, off offset:512
	v_mul_f32_e32 v32, 0xbfb8aa3b, v52
	v_exp_f32_e32 v32, v32
	s_mov_b32 s48, 0x63000
	v_add_f32_e32 v32, 1.0, v32
	v_rcp_f32_e32 v32, v32
	s_nop 0
	v_mul_f32_e32 v32, v52, v32
	v_mul_f32_e32 v32, v36, v32
	v_cvt_pk_bf16_f32 v34, v32, s0
	v_lshl_add_u64 v[32:33], v[128:129], 0, s[48:49]
	global_store_short v[32:33], v34, off
	v_mul_f32_e32 v32, 0xbfb8aa3b, v53
	v_exp_f32_e32 v32, v32
	s_mov_b32 s48, 0x64000
	v_add_f32_e32 v32, 1.0, v32
	v_rcp_f32_e32 v32, v32
	s_nop 0
	v_mul_f32_e32 v32, v53, v32
	v_mul_f32_e32 v32, v37, v32
	v_cvt_pk_bf16_f32 v34, v32, s0
	v_lshl_add_u64 v[32:33], v[128:129], 0, s[48:49]
	global_store_short v[32:33], v34, off offset:1536
	v_mul_f32_e32 v32, 0xbfb8aa3b, v54
	v_exp_f32_e32 v32, v32
	s_mov_b32 s48, 0x65000
	v_add_f32_e32 v32, 1.0, v32
	v_rcp_f32_e32 v32, v32
	s_nop 0
	v_mul_f32_e32 v32, v54, v32
	v_mul_f32_e32 v32, v38, v32
	v_cvt_pk_bf16_f32 v34, v32, s0
	v_lshl_add_u64 v[32:33], v[128:129], 0, s[48:49]
	global_store_short v[32:33], v34, off offset:3072
	v_mul_f32_e32 v32, 0xbfb8aa3b, v55
	v_exp_f32_e32 v32, v32
	s_mov_b32 s48, 0x67000
	v_add_f32_e32 v32, 1.0, v32
	v_rcp_f32_e32 v32, v32
	s_nop 0
	v_mul_f32_e32 v32, v55, v32
	v_mul_f32_e32 v32, v39, v32
	v_cvt_pk_bf16_f32 v34, v32, s0
	v_lshl_add_u64 v[32:33], v[128:129], 0, s[48:49]
	global_store_short v[32:33], v34, off offset:512
	v_mul_f32_e32 v32, 0xbfb8aa3b, v56
	v_exp_f32_e32 v32, v32
	s_mov_b32 s48, 0x6e000
	v_add_f32_e32 v32, 1.0, v32
	v_rcp_f32_e32 v32, v32
	s_nop 0
	v_mul_f32_e32 v32, v56, v32
	v_mul_f32_e32 v32, v40, v32
	v_cvt_pk_bf16_f32 v34, v32, s0
	v_lshl_add_u64 v[32:33], v[128:129], 0, s[48:49]
	global_store_short v[32:33], v34, off
	v_mul_f32_e32 v32, 0xbfb8aa3b, v57
	v_exp_f32_e32 v32, v32
	s_mov_b32 s48, 0x6f000
	v_add_f32_e32 v32, 1.0, v32
	v_rcp_f32_e32 v32, v32
	s_nop 0
	v_mul_f32_e32 v32, v57, v32
	v_mul_f32_e32 v32, v41, v32
	v_cvt_pk_bf16_f32 v34, v32, s0
	v_lshl_add_u64 v[32:33], v[128:129], 0, s[48:49]
	global_store_short v[32:33], v34, off offset:1536
	v_mul_f32_e32 v32, 0xbfb8aa3b, v58
	v_exp_f32_e32 v32, v32
	s_mov_b32 s48, 0x70000
	v_add_f32_e32 v32, 1.0, v32
	v_rcp_f32_e32 v32, v32
	s_nop 0
	v_mul_f32_e32 v32, v58, v32
	v_mul_f32_e32 v32, v42, v32
	v_cvt_pk_bf16_f32 v34, v32, s0
	v_lshl_add_u64 v[32:33], v[128:129], 0, s[48:49]
	global_store_short v[32:33], v34, off offset:3072
	v_mul_f32_e32 v32, 0xbfb8aa3b, v59
	v_exp_f32_e32 v32, v32
	s_mov_b32 s48, 0x72000
	v_add_f32_e32 v32, 1.0, v32
	v_rcp_f32_e32 v32, v32
	s_nop 0
	v_mul_f32_e32 v32, v59, v32
	v_mul_f32_e32 v32, v43, v32
	v_cvt_pk_bf16_f32 v34, v32, s0
	v_lshl_add_u64 v[32:33], v[128:129], 0, s[48:49]
	global_store_short v[32:33], v34, off offset:512
	v_mul_f32_e32 v32, 0xbfb8aa3b, v60
	v_exp_f32_e32 v32, v32
	s_mov_b32 s48, 0x79000
	v_add_f32_e32 v32, 1.0, v32
	v_rcp_f32_e32 v32, v32
	s_nop 0
	v_mul_f32_e32 v32, v60, v32
	v_mul_f32_e32 v32, v44, v32
	v_cvt_pk_bf16_f32 v34, v32, s0
	v_lshl_add_u64 v[32:33], v[128:129], 0, s[48:49]
	global_store_short v[32:33], v34, off
	v_mul_f32_e32 v32, 0xbfb8aa3b, v61
	v_exp_f32_e32 v32, v32
	s_mov_b32 s48, 0x7a000
	v_add_f32_e32 v32, 1.0, v32
	v_rcp_f32_e32 v32, v32
	s_nop 0
	v_mul_f32_e32 v32, v61, v32
	v_mul_f32_e32 v32, v45, v32
	v_cvt_pk_bf16_f32 v34, v32, s0
	v_lshl_add_u64 v[32:33], v[128:129], 0, s[48:49]
	global_store_short v[32:33], v34, off offset:1536
	v_mul_f32_e32 v32, 0xbfb8aa3b, v62
	v_exp_f32_e32 v32, v32
	s_mov_b32 s48, 0x7b000
	v_add_f32_e32 v32, 1.0, v32
	v_rcp_f32_e32 v32, v32
	s_nop 0
	v_mul_f32_e32 v32, v62, v32
	v_mul_f32_e32 v32, v46, v32
	v_cvt_pk_bf16_f32 v34, v32, s0
	v_lshl_add_u64 v[32:33], v[128:129], 0, s[48:49]
	global_store_short v[32:33], v34, off offset:3072
	v_mul_f32_e32 v32, 0xbfb8aa3b, v63
	v_exp_f32_e32 v32, v32
	s_mov_b32 s48, 0x7d000
	v_add_f32_e32 v32, 1.0, v32
	v_rcp_f32_e32 v32, v32
	s_nop 0
	v_mul_f32_e32 v32, v63, v32
	v_mul_f32_e32 v32, v47, v32
	v_cvt_pk_bf16_f32 v34, v32, s0
	v_lshl_add_u64 v[32:33], v[128:129], 0, s[48:49]
	global_store_short v[32:33], v34, off offset:512
	v_mul_f32_e32 v32, 0xbfb8aa3b, v16
	v_exp_f32_e32 v32, v32
	s_mov_b32 s48, 0x84000
; template <bool RES, class Epi>
; DEV void gemm_tile_x(const bf16_t* A0, int lda0, const bf16_t* A1, int lda1, int ksplit,
;                      const bf16_t* Bt, int ldb, int K, char* smem, const float* resb, Epi epi) {
;     ...
;   for (int mi = 0; mi < 4; ++mi) {
; #pragma unroll
;     for (int rh = 0; rh < 2; ++rh) {
;       float x0[8], x1[8];
;       if (RES) {
; #pragma unroll
;         for (int r8 = 0; r8 < 8; ++r8) {
;           const int r = rh * 8 + r8;
;           const int ru = mi * 32 + (r & 3) + 8 * (r >> 2);
;           const float* rp = resb + ru * DM;
;           x0[r8] = rp[resoff];
;           x1[r8] = rp[resoff + 32];
;         }
;       }
; #pragma unroll
;       for (int r8 = 0; r8 < 8; ++r8) {
;         const int r = rh * 8 + r8;
;         const int ru = mi * 32 + (r & 3) + 8 * (r >> 2);
;         if (RES) epi(ru, rl, col, acc[mi][0][r], acc[mi][1][r], x0[r8], x1[r8]);
;         else epi(ru, rl, col, acc[mi][0][r], acc[mi][1][r], 0.f, 0.f);
;         if ((r8 & 3) == 3) __builtin_amdgcn_sched_barrier(0);
;       }
; DEV bool tile_map(int it, int nct, int& rt, int& ct) {
;   const int bpx = gridDim.x >> 3, xcd = blockIdx.x & 7, j = blockIdx.x >> 3;
;   const int q = j + it * bpx;
;   if (q >= 24 * nct) return false;
;   const int band = q / (4 * nct), qq = q - band * 4 * nct;
;   rt = xcd * 24 + band * 4 + (qq & 3);
;   ct = qq >> 2;
;   return true;
	v_add_f32_e32 v32, 1.0, v32
	v_rcp_f32_e32 v32, v32
	s_nop 0
	v_mul_f32_e32 v16, v16, v32
	v_mul_f32_e32 v0, v0, v16
	v_lshl_add_u64 v[32:33], v[128:129], 0, s[48:49]
	v_cvt_pk_bf16_f32 v0, v0, s0
	s_nop 0
	global_store_short v[32:33], v0, off
	v_mul_f32_e32 v0, 0xbfb8aa3b, v17
	v_exp_f32_e32 v0, v0
	s_mov_b32 s48, 0x85000
	v_add_f32_e32 v0, 1.0, v0
	v_rcp_f32_e32 v0, v0
	s_nop 0
	v_mul_f32_e32 v0, v17, v0
	v_mul_f32_e32 v0, v1, v0
	v_cvt_pk_bf16_f32 v16, v0, s0
	v_lshl_add_u64 v[0:1], v[128:129], 0, s[48:49]
	global_store_short v[0:1], v16, off offset:1536
	v_mul_f32_e32 v0, 0xbfb8aa3b, v18
	v_exp_f32_e32 v0, v0
	s_mov_b32 s48, 0x86000
	v_add_f32_e32 v0, 1.0, v0
	v_rcp_f32_e32 v0, v0
	s_nop 0
	v_mul_f32_e32 v0, v18, v0
	v_mul_f32_e32 v0, v2, v0
	v_cvt_pk_bf16_f32 v2, v0, s0
	v_lshl_add_u64 v[0:1], v[128:129], 0, s[48:49]
	global_store_short v[0:1], v2, off offset:3072
	v_mul_f32_e32 v0, 0xbfb8aa3b, v19
	v_exp_f32_e32 v0, v0
	s_mov_b32 s48, 0x88000
	v_add_f32_e32 v0, 1.0, v0
	v_rcp_f32_e32 v0, v0
	s_nop 0
	v_mul_f32_e32 v0, v19, v0
	v_mul_f32_e32 v0, v3, v0
	v_cvt_pk_bf16_f32 v2, v0, s0
	v_lshl_add_u64 v[0:1], v[128:129], 0, s[48:49]
	global_store_short v[0:1], v2, off offset:512
	v_mul_f32_e32 v0, 0xbfb8aa3b, v20
	v_exp_f32_e32 v0, v0
	s_mov_b32 s48, 0x8f000
	v_add_f32_e32 v0, 1.0, v0
	v_rcp_f32_e32 v0, v0
	s_nop 0
	v_mul_f32_e32 v0, v20, v0
	v_mul_f32_e32 v0, v4, v0
	v_cvt_pk_bf16_f32 v2, v0, s0
	v_lshl_add_u64 v[0:1], v[128:129], 0, s[48:49]
	global_store_short v[0:1], v2, off
	v_mul_f32_e32 v0, 0xbfb8aa3b, v21
	v_exp_f32_e32 v0, v0
	s_mov_b32 s48, 0x90000
	v_add_f32_e32 v0, 1.0, v0
	v_rcp_f32_e32 v0, v0
	s_nop 0
	v_mul_f32_e32 v0, v21, v0
	v_mul_f32_e32 v0, v5, v0
	v_cvt_pk_bf16_f32 v2, v0, s0
	v_lshl_add_u64 v[0:1], v[128:129], 0, s[48:49]
	global_store_short v[0:1], v2, off offset:1536
	v_mul_f32_e32 v0, 0xbfb8aa3b, v22
	v_exp_f32_e32 v0, v0
	s_mov_b32 s48, 0x91000
	v_add_f32_e32 v0, 1.0, v0
	v_rcp_f32_e32 v0, v0
	s_nop 0
	v_mul_f32_e32 v0, v22, v0
	v_mul_f32_e32 v0, v6, v0
	v_cvt_pk_bf16_f32 v2, v0, s0
	v_lshl_add_u64 v[0:1], v[128:129], 0, s[48:49]
	global_store_short v[0:1], v2, off offset:3072
	v_mul_f32_e32 v0, 0xbfb8aa3b, v23
	v_exp_f32_e32 v0, v0
	s_mov_b32 s48, 0x93000
	v_add_f32_e32 v0, 1.0, v0
	v_rcp_f32_e32 v0, v0
	s_nop 0
	v_mul_f32_e32 v0, v23, v0
	v_mul_f32_e32 v0, v7, v0
	v_cvt_pk_bf16_f32 v2, v0, s0
	v_lshl_add_u64 v[0:1], v[128:129], 0, s[48:49]
	global_store_short v[0:1], v2, off offset:512
	v_mul_f32_e32 v0, 0xbfb8aa3b, v24
	v_exp_f32_e32 v0, v0
	s_mov_b32 s48, 0x9a000
	v_add_f32_e32 v0, 1.0, v0
	v_rcp_f32_e32 v0, v0
	s_nop 0
	v_mul_f32_e32 v0, v24, v0
	v_mul_f32_e32 v0, v8, v0
	v_cvt_pk_bf16_f32 v2, v0, s0
	v_lshl_add_u64 v[0:1], v[128:129], 0, s[48:49]
	global_store_short v[0:1], v2, off
	v_mul_f32_e32 v0, 0xbfb8aa3b, v25
	v_exp_f32_e32 v0, v0
	s_mov_b32 s48, 0x9b000
	v_add_f32_e32 v0, 1.0, v0
	v_rcp_f32_e32 v0, v0
	s_nop 0
	v_mul_f32_e32 v0, v25, v0
	v_mul_f32_e32 v0, v9, v0
	v_cvt_pk_bf16_f32 v2, v0, s0
	v_lshl_add_u64 v[0:1], v[128:129], 0, s[48:49]
	global_store_short v[0:1], v2, off offset:1536
	v_mul_f32_e32 v0, 0xbfb8aa3b, v26
	v_exp_f32_e32 v0, v0
	s_mov_b32 s48, 0x9c000
	v_add_f32_e32 v0, 1.0, v0
	v_rcp_f32_e32 v0, v0
	s_nop 0
	v_mul_f32_e32 v0, v26, v0
	v_mul_f32_e32 v0, v10, v0
	v_cvt_pk_bf16_f32 v2, v0, s0
	v_lshl_add_u64 v[0:1], v[128:129], 0, s[48:49]
	global_store_short v[0:1], v2, off offset:3072
	v_mul_f32_e32 v0, 0xbfb8aa3b, v27
	v_exp_f32_e32 v0, v0
	s_mov_b32 s48, 0x9e000
	v_add_f32_e32 v0, 1.0, v0
	v_rcp_f32_e32 v0, v0
	s_nop 0
	v_mul_f32_e32 v0, v27, v0
	v_mul_f32_e32 v0, v11, v0
	v_cvt_pk_bf16_f32 v2, v0, s0
	v_lshl_add_u64 v[0:1], v[128:129], 0, s[48:49]
	global_store_short v[0:1], v2, off offset:512
	v_mul_f32_e32 v0, 0xbfb8aa3b, v28
	v_exp_f32_e32 v0, v0
	s_mov_b32 s48, 0xa5000
	v_add_f32_e32 v0, 1.0, v0
	v_rcp_f32_e32 v0, v0
	s_nop 0
	v_mul_f32_e32 v0, v28, v0
	v_mul_f32_e32 v0, v12, v0
	v_cvt_pk_bf16_f32 v2, v0, s0
	v_lshl_add_u64 v[0:1], v[128:129], 0, s[48:49]
	global_store_short v[0:1], v2, off
	v_mul_f32_e32 v0, 0xbfb8aa3b, v29
	v_exp_f32_e32 v0, v0
	s_mov_b32 s48, 0xa6000
	v_add_f32_e32 v0, 1.0, v0
	v_rcp_f32_e32 v0, v0
	s_nop 0
	v_mul_f32_e32 v0, v29, v0
	v_mul_f32_e32 v0, v13, v0
	v_cvt_pk_bf16_f32 v2, v0, s0
	v_lshl_add_u64 v[0:1], v[128:129], 0, s[48:49]
	global_store_short v[0:1], v2, off offset:1536
	v_mul_f32_e32 v0, 0xbfb8aa3b, v30
	v_exp_f32_e32 v0, v0
	s_mov_b32 s48, 0xa7000
	v_add_f32_e32 v0, 1.0, v0
	v_rcp_f32_e32 v0, v0
	s_nop 0
	v_mul_f32_e32 v0, v30, v0
	v_mul_f32_e32 v0, v14, v0
	v_cvt_pk_bf16_f32 v2, v0, s0
	v_lshl_add_u64 v[0:1], v[128:129], 0, s[48:49]
	global_store_short v[0:1], v2, off offset:3072
	v_mul_f32_e32 v0, 0xbfb8aa3b, v31
	v_exp_f32_e32 v0, v0
	s_nop 0
	v_add_f32_e32 v0, 1.0, v0
	v_rcp_f32_e32 v0, v0
	s_nop 0
	v_mul_f32_e32 v0, v31, v0
	v_mul_f32_e32 v0, v15, v0
	v_cvt_pk_bf16_f32 v2, v0, s0
	v_add_co_u32_e32 v0, vcc, 0xa9000, v128
	s_nop 1
	v_addc_co_u32_e32 v1, vcc, 0, v129, vcc
	global_store_short v[0:1], v2, off offset:512
	s_add_i32 s58, s58, 1
	s_mul_i32 s48, s58, s86
	s_add_i32 s48, s48, s87
	s_cmpk_lt_u32 s48, 0x420
	s_cbranch_scc0 .LBB0_183
